# layer-0 out-projection: context split-K units run before the main tile and signal a completion counter; the grid barrier before ctx_norm replaced by a poll of that counter (one grid barrier fewer)
# baseline (speedup 1.0000x reference)
.LBB0_196:
	s_mov_b32 s6, 1
	s_nop 0
	v_writelane_b32 v255, s6, 10
	s_mov_b32 s6, 0
	s_nop 0
	v_writelane_b32 v255, s6, 12
	s_mov_b32 s14, s2

.Lp4_resetup:
	s_mul_i32 s12, s71, 0x7800
	s_lshl_b64 s[4:5], s[12:13], 2
	v_readlane_b32 s6, v252, 9
	v_readlane_b32 s7, v252, 10
	s_add_u32 s4, s6, s4
	s_addc_u32 s5, s7, s5
	v_writelane_b32 v254, s4, 57
	v_readlane_b32 s6, v253, 0
	v_readlane_b32 s7, v253, 1
	v_writelane_b32 v254, s5, 58
	s_mul_i32 s12, s71, 0x4400
	v_readlane_b32 s4, v254, 51
	s_add_u32 s40, s4, 0x300000
	v_readlane_b32 s4, v254, 52
	s_addc_u32 s41, s4, 0
	s_lshl_b32 s10, s71, 2
	s_mul_i32 s4, s71, 0x110000
	s_add_u32 s4, s6, s4
	s_addc_u32 s5, s7, 0
	v_writelane_b32 v254, s4, 59
	v_readlane_b32 s8, v253, 2
	v_readlane_b32 s9, v253, 3
	v_writelane_b32 v254, s5, 60
	s_lshl_b64 s[4:5], s[12:13], 2
	s_add_u32 s21, s8, s4
	s_addc_u32 s4, s9, s5
	v_writelane_b32 v254, s4, 61
	s_or_b32 s4, s10, 1
	s_mul_i32 s5, s4, 0x44000
	v_writelane_b32 v254, s10, 63
	s_add_u32 s34, s6, s5
	s_mul_i32 s12, s4, 0x1100
	s_addc_u32 s35, s7, 0
	s_lshl_b64 s[4:5], s[12:13], 2
	v_readlane_b32 s6, v254, 53
	s_add_u32 s15, s8, s4
	v_readlane_b32 s7, v254, 54
	s_addc_u32 s16, s9, s5
	s_and_b64 vcc, exec, s[6:7]
	v_readlane_b32 s6, v253, 6
	v_readlane_b32 s7, v253, 7
	s_mov_b64 s[4:5], -1
	s_mov_b32 s71, 0x400000
	v_cndmask_b32_e64 v0, 0, 1, s[6:7]
	v_cmp_ne_u32_e64 s[6:7], 1, v0
	s_waitcnt lgkmcnt(0)
	s_barrier
	v_writelane_b32 v255, s6, 0
	s_nop 1
	v_writelane_b32 v255, s7, 1
	v_readlane_b32 s100, v255, 12
	s_nop 0
	s_cmp_lg_u32 s100, 0
	s_cbranch_scc1 .Lp4_main
	v_readlane_b32 s100, v254, 55
	v_readlane_b32 s101, v254, 56
	s_nop 0
	s_cmp_lg_u64 s[100:101], 0
	s_cbranch_scc0 .Lp4_main
	s_mov_b32 s100, 1
	s_nop 0
	v_writelane_b32 v255, s100, 12
	s_branch .LBB0_812
.Lp4_main:
	s_cbranch_vccz .LBB0_708
	v_readlane_b32 s4, v255, 0
	v_mbcnt_lo_u32_b32 v0, -1, 0
	v_mbcnt_hi_u32_b32 v0, -1, v0
	v_readlane_b32 s5, v255, 1
	v_add_u32_e32 v216, s33, v0
	s_and_b64 vcc, exec, s[4:5]
	v_readfirstlane_b32 s19, v216
	s_cbranch_vccnz .LBB0_707
	v_lshlrev_b32_e32 v0, 4, v216
	s_waitcnt vmcnt(0)
	v_add_u32_e32 v3, 0x2000, v0
	v_ashrrev_i32_e32 v2, 31, v3
	v_lshrrev_b32_e32 v2, 22, v2
	v_add_u32_e32 v2, v3, v2
	v_ashrrev_i32_e32 v2, 10, v2
	v_mul_i32_i24_e32 v4, 0x400, v2
	v_sub_u32_e32 v3, v3, v4
	v_lshrrev_b32_e32 v4, 4, v3
	v_bitop3_b32 v4, v4, v3, 32 bitop3:0x6c
	v_ashrrev_i32_e32 v3, 31, v4
	v_lshrrev_b32_e32 v3, 26, v3
	v_add_u32_e32 v5, v4, v3
	v_lshlrev_b32_e32 v6, 3, v2
	v_ashrrev_i32_e32 v3, 6, v5
	v_and_b32_e32 v6, -16, v6
	v_add_u32_e32 v6, v3, v6
	v_and_b32_e32 v7, 3, v3
	s_mov_b32 s4, 0x1fffe0
	v_lshrrev_b32_e32 v8, 2, v6
	v_lshlrev_b32_e32 v9, 1, v6
	v_and_b32_e32 v5, 0xc0, v5
	v_and_or_b32 v7, v6, s4, v7
	v_and_b32_e32 v8, 4, v8
	v_and_b32_e32 v9, 24, v9
	v_sub_u32_e32 v4, v4, v5
	v_or3_b32 v7, v7, v8, v9
	v_lshlrev_b32_e32 v8, 5, v2
	v_ashrrev_i16_sdwa v4, v222, sext(v4) dst_sel:DWORD dst_unused:UNUSED_PAD src0_sel:DWORD src1_sel:BYTE_0
	v_and_b32_e32 v8, 32, v8
	v_bfe_i32 v4, v4, 0, 16
	v_add_lshl_u32 v5, v8, v4, 1
	v_lshl_add_u32 v132, v7, 11, v5
	v_lshl_add_u32 v134, v6, 11, v5
	v_bfe_i32 v5, v216, 27, 1
	v_lshrrev_b32_e32 v5, 22, v5
	v_add_u32_e32 v5, v0, v5
	v_and_b32_e32 v5, 0xfffffc00, v5
	v_sub_u32_e32 v0, v0, v5
	v_lshrrev_b32_e32 v5, 4, v0
	v_ashrrev_i32_e32 v6, 31, v216
	v_bitop3_b32 v0, v5, v0, 32 bitop3:0x6c
	v_lshrrev_b32_e32 v6, 26, v6
	v_ashrrev_i32_e32 v5, 31, v0
	v_add_u32_e32 v6, v216, v6
	v_lshrrev_b32_e32 v5, 26, v5
	v_ashrrev_i32_e32 v6, 6, v6
	v_add_u32_e32 v7, v0, v5
	v_lshlrev_b32_e32 v8, 3, v6
	v_ashrrev_i32_e32 v5, 6, v7
	v_and_b32_e32 v8, -16, v8
	v_add_u32_e32 v8, v5, v8
	v_and_b32_e32 v9, 3, v5
	v_lshrrev_b32_e32 v10, 2, v8
	v_lshlrev_b32_e32 v11, 1, v8
	v_and_b32_e32 v7, 0xc0, v7
	s_ashr_i32 s8, s19, 6
	v_and_or_b32 v9, v8, s4, v9
	v_and_b32_e32 v10, 4, v10
	v_and_b32_e32 v11, 24, v11
	v_sub_u32_e32 v0, v0, v7
	s_ashr_i32 s36, s19, 8
	s_lshl_b32 s38, s8, 10
	v_or3_b32 v9, v9, v10, v11
	v_lshlrev_b32_e32 v10, 5, v6
	v_ashrrev_i16_sdwa v0, v222, sext(v0) dst_sel:DWORD dst_unused:UNUSED_PAD src0_sel:DWORD src1_sel:BYTE_0
	v_readlane_b32 s4, v253, 56
	v_and_b32_e32 v10, 32, v10
	v_bfe_i32 v7, v0, 0, 16
	v_readlane_b32 s5, v253, 57
	s_add_u32 s4, s40, s4
	v_add_lshl_u32 v10, v10, v7, 1
	s_addc_u32 s5, s41, s5
	s_add_i32 s71, s38, 0
	v_lshl_add_u32 v0, v9, 11, v10
	s_add_i32 m0, s71, 0x10000
	v_lshl_add_u32 v136, v8, 11, v10
	global_load_lds_dwordx4 v0, s[4:5]
	s_add_i32 m0, s71, 0x12000
	s_add_u32 s6, s4, 0x40000
	global_load_lds_dwordx4 v132, s[4:5]
	s_addc_u32 s7, s5, 0
	s_add_i32 m0, s71, 0x14000
	s_add_i32 s39, s71, 0x2000
	global_load_lds_dwordx4 v0, s[6:7]
	s_add_i32 m0, s71, 0x16000
	s_add_i32 s37, s71, 0x4000
	global_load_lds_dwordx4 v132, s[6:7]
	v_readlane_b32 s6, v253, 58
	s_mov_b32 m0, s71
	v_readlane_b32 s7, v253, 59
	s_add_i32 s14, s71, 0x6000
	v_writelane_b32 v255, s21, 2
	v_writelane_b32 v255, s16, 3
	v_writelane_b32 v255, s15, 4
	v_writelane_b32 v255, s34, 5
	global_load_lds_dwordx4 v136, s[6:7]
	s_mov_b32 m0, s39
	v_writelane_b32 v255, s35, 6
	global_load_lds_dwordx4 v134, s[6:7]
	v_readlane_b32 s6, v253, 60
	s_mov_b32 m0, s37
	v_readlane_b32 s7, v253, 61
	s_cmp_lg_u32 s36, 1
	s_nop 3
	global_load_lds_dwordx4 v136, s[6:7]
	s_mov_b32 m0, s14
	s_nop 0
	global_load_lds_dwordx4 v134, s[6:7]
	s_cbranch_scc1 .LBB0_607
	s_barrier

.LBB0_812:
	v_readlane_b32 s4, v254, 55
	v_readlane_b32 s5, v254, 56
	s_andn2_b64 vcc, exec, s[4:5]
	s_nop 0
	v_cndmask_b32_e64 v0, 0, 1, s[4:5]
	v_cmp_ne_u32_e64 s[6:7], 1, v0
	s_nop 1
	v_writelane_b32 v254, s6, 61
	s_nop 1
	v_writelane_b32 v254, s7, 62
	s_cbranch_vccnz .LBB0_880
	v_readlane_b32 s100, v255, 12
	s_nop 0
	s_cmp_eq_u32 s100, 2
	s_cbranch_scc0 .Lp4_split
	s_mov_b32 s100, 0
	s_nop 0
	v_writelane_b32 v255, s100, 12
	s_branch .LBB0_830
.Lp4_split:
	v_readlane_b32 s4, v253, 8
	s_waitcnt lgkmcnt(0)
	s_barrier
	v_mbcnt_lo_u32_b32 v0, -1, 0
	v_mbcnt_hi_u32_b32 v0, -1, v0
	v_readlane_b32 s5, v253, 9
	s_waitcnt vmcnt(0)
	v_add_u32_e32 v2, s33, v0
	s_andn2_b64 vcc, exec, s[4:5]
	v_readfirstlane_b32 s4, v2
	s_cbranch_vccnz .LBB0_831
	v_lshlrev_b32_e32 v0, 4, v2
	v_add_u32_e32 v3, 0x2000, v0
	v_ashrrev_i32_e32 v4, 31, v3
	v_lshrrev_b32_e32 v4, 22, v4
	v_add_u32_e32 v4, v3, v4
	v_ashrrev_i32_e32 v4, 10, v4
	v_mul_i32_i24_e32 v5, 0x400, v4
	v_sub_u32_e32 v3, v3, v5
	v_lshrrev_b32_e32 v5, 4, v3
	v_bitop3_b32 v3, v5, v3, 32 bitop3:0x6c
	v_ashrrev_i32_e32 v5, 31, v3
	v_lshrrev_b32_e32 v5, 26, v5
	v_add_u32_e32 v5, v3, v5
	v_lshrrev_b32_e32 v6, 6, v5
	v_lshlrev_b32_e32 v7, 3, v4
	v_and_b32_e32 v5, 0xc0, v5
	v_and_b32_e32 v7, 0x1ffff0, v7
	v_lshlrev_b32_e32 v4, 5, v4
	v_sub_u32_e32 v3, v3, v5
	v_add_u32_e32 v6, v6, v7
	v_and_b32_e32 v4, 32, v4
	v_ashrrev_i16_sdwa v3, v222, sext(v3) dst_sel:DWORD dst_unused:UNUSED_PAD src0_sel:DWORD src1_sel:BYTE_0
	v_lshl_or_b32 v4, v6, 10, v4
	v_bfe_i32 v3, v3, 0, 16
	v_add_lshl_u32 v130, v4, v3, 1
	v_bfe_i32 v3, v2, 27, 1
	v_lshrrev_b32_e32 v3, 22, v3
	v_add_u32_e32 v3, v0, v3
	v_and_b32_e32 v3, 0xfffffc00, v3
	v_sub_u32_e32 v0, v0, v3
	v_lshrrev_b32_e32 v3, 4, v0
	v_bitop3_b32 v0, v3, v0, 32 bitop3:0x6c
	v_ashrrev_i32_e32 v5, 31, v2
	v_ashrrev_i32_e32 v3, 31, v0
	v_lshrrev_b32_e32 v5, 26, v5
	s_ashr_i32 s8, s4, 6
	v_lshrrev_b32_e32 v3, 26, v3
	v_add_u32_e32 v5, v2, v5
	s_ashr_i32 s5, s4, 8
	s_lshl_b32 s6, s8, 10
	v_add_u32_e32 v3, v0, v3
	v_ashrrev_i32_e32 v5, 6, v5
	v_readlane_b32 s10, v253, 17
	v_lshrrev_b32_e32 v4, 6, v3
	v_lshlrev_b32_e32 v6, 3, v5
	v_and_b32_e32 v3, 0xc0, v3
	v_readlane_b32 s11, v253, 18
	s_add_u32 s7, s40, s10
	v_and_b32_e32 v6, 0x1ffff0, v6
	v_lshlrev_b32_e32 v5, 5, v5
	v_sub_u32_e32 v0, v0, v3
	s_addc_u32 s9, s41, s11
	v_readlane_b32 s10, v253, 19
	v_add_u32_e32 v4, v4, v6
	v_and_b32_e32 v5, 32, v5
	v_ashrrev_i16_sdwa v0, v222, sext(v0) dst_sel:DWORD dst_unused:UNUSED_PAD src0_sel:DWORD src1_sel:BYTE_0
	s_add_u32 s24, s7, s10
	v_readlane_b32 s7, v253, 20
	v_lshl_or_b32 v4, v4, 10, v5
	v_bfe_i32 v0, v0, 0, 16
	s_addc_u32 s25, s9, s7
	s_add_i32 s7, s6, 0
	v_add_lshl_u32 v0, v4, v0, 1
	s_add_i32 m0, s7, 0x10000
	s_nop 0
	global_load_lds_dwordx4 v0, s[24:25]
	s_add_i32 m0, s7, 0x12000
	s_add_u32 s10, s24, 0x40000
	global_load_lds_dwordx4 v130, s[24:25]
	s_addc_u32 s11, s25, 0
	s_add_i32 m0, s7, 0x14000
	s_add_i32 s12, s7, 0x2000
	global_load_lds_dwordx4 v0, s[10:11]
	s_add_i32 m0, s7, 0x16000
	s_add_i32 s28, s7, 0x4000
	global_load_lds_dwordx4 v130, s[10:11]
	v_readlane_b32 s10, v253, 21
	s_mov_b32 m0, s7
	v_readlane_b32 s11, v253, 22
	s_add_i32 s29, s7, 0x6000
	s_cmp_eq_u32 s5, 1
	s_nop 2
	global_load_lds_dwordx4 v0, s[10:11]
	s_mov_b32 m0, s12
	s_nop 0
	global_load_lds_dwordx4 v130, s[10:11]
	v_readlane_b32 s10, v253, 23
	s_mov_b32 m0, s28
	v_readlane_b32 s11, v253, 24
	s_nop 4
	global_load_lds_dwordx4 v0, s[10:11]
	s_mov_b32 m0, s29
	s_nop 0
	global_load_lds_dwordx4 v130, s[10:11]
	s_cselect_b64 s[10:11], -1, 0
	s_cmp_lg_u32 s5, 1
	s_cbranch_scc1 .LBB0_816
	s_barrier

.LBB0_831:
	v_readlane_b32 s100, v255, 12
	s_nop 0
	s_cmp_eq_u32 s100, 1
	s_cbranch_scc0 .Lp4_bar_a
	s_mov_b32 s100, 2
	s_nop 0
	v_writelane_b32 v255, s100, 12
	v_readlane_b32 s71, v254, 63
	s_nop 0
	s_lshr_b32 s71, s71, 2
	s_mov_b64 s[100:101], exec
	s_mov_b64 exec, 1
	v_mov_b32_e32 v2, 0x80000
	v_mov_b32_e32 v3, 1
	global_atomic_add v2, v3, s[46:47]
	s_mov_b64 exec, s[100:101]
	s_branch .Lp4_resetup

.LBB0_833:
	s_waitcnt vmcnt(0)
	s_waitcnt vmcnt(0) lgkmcnt(0)
	s_barrier
	s_and_saveexec_b64 s[4:5], s[8:9]
	s_cbranch_execz .LBB0_877
	v_mov_b32_e32 v2, 0x80000
	s_mov_b32 s6, 0x40000
.Lp4c_poll:
	global_load_dword v3, v2, s[46:47] sc1
	s_waitcnt vmcnt(0)
	v_readfirstlane_b32 s7, v3
	s_nop 0
	s_cmp_ge_u32 s7, 0x200
	s_cbranch_scc1 .Lp4c_ok
	s_sleep 1
	s_sub_u32 s6, s6, 1
	s_cmp_lg_u32 s6, 0
	s_cbranch_scc1 .Lp4c_poll
.Lp4c_ok:
	buffer_inv sc1
	s_waitcnt vmcnt(0)
